# v47: gdn_prep gate-input loads issued at job start; f32 MFMA loop unrolled with operand reads 7 pairs ahead
# speedup vs baseline: 1.2058x; 1.0016x over previous
.LBB0_2860:
	s_mul_hi_i32 s0, s72, 0x7e07e07f
	s_lshr_b32 s1, s0, 31
	s_ashr_i32 s0, s0, 5
	s_add_i32 s0, s0, s1
	s_mul_i32 s1, s0, 0x41
	s_sub_i32 s1, s72, s1
	s_and_b32 s40, s0, 7
	s_lshr_b32 s41, s0, 3
	s_lshl_b32 s0, s1, 6
	s_sub_i32 s46, s0, 48
	v_add_u32_e32 v41, s46, v39
	s_mulk_i32 s41, 0x1010
	s_lshl_b32 s76, s40, 2
	s_mov_b64 s[98:99], exec
	s_and_b64 exec, exec, s[2:3]
	v_add_u32_e32 v244, s46, v208
	v_cmp_lt_i32_e64 s[100:101], -1, v244
	s_and_b64 exec, exec, s[100:101]
	v_add_u32_e32 v244, s41, v244
	v_ashrrev_i32_e32 v245, 31, v244
	v_lshlrev_b64 v[244:245], 6, v[244:245]
	v_lshl_add_u64 v[244:245], s[78:79], 0, v[244:245]
	v_lshl_add_u64 v[244:245], v[244:245], 0, s[76:77]
	v_mov_b32_e32 v246, s76
	global_load_dword v252, v246, s[86:87]
	global_load_dword v253, v246, s[84:85]
	global_load_dword v242, v[244:245], off offset:32
	global_load_dword v243, v[244:245], off
	s_mov_b64 exec, s[98:99]
	v_max_i32_e32 v0, 2, v41
	v_lshl_or_b32 v4, s40, 6, v16
	v_add3_u32 v0, s41, -2, v0
	v_lshlrev_b32_e32 v20, 2, v4
	v_ashrrev_i32_e32 v1, 31, v0
	v_lshl_add_u64 v[48:49], s[82:83], 0, v[20:21]
	s_movk_i32 s0, 0x1000
	v_lshlrev_b64 v[0:1], 12, v[0:1]
	v_add_co_u32_e32 v50, vcc, s0, v48
	s_barrier
	v_lshl_add_u64 v[0:1], s[42:43], 0, v[0:1]
	s_waitcnt lgkmcnt(0)
	v_max_i32_e32 v2, 1, v41
	v_addc_co_u32_e32 v51, vcc, 0, v49, vcc
	global_load_dword v63, v20, s[82:83]
	global_load_dword v62, v[50:51], off offset:2048
	v_lshlrev_b32_e32 v20, 1, v4
	v_cmp_lt_i32_e64 s[34:35], -1, v41
	v_add3_u32 v2, s41, -1, v2
	v_add_u32_e32 v6, 0x1a0, v4
	v_lshl_add_u64 v[4:5], v[0:1], 0, v[20:21]
	v_cndmask_b32_e64 v0, 0, v41, s[34:35]
	v_ashrrev_i32_e32 v3, 31, v2
	v_add_u32_e32 v0, s41, v0
	v_lshlrev_b64 v[2:3], 12, v[2:3]
	v_ashrrev_i32_e32 v1, 31, v0
	v_lshl_add_u64 v[2:3], s[42:43], 0, v[2:3]
	v_lshlrev_b64 v[0:1], 12, v[0:1]
	v_add_co_u32_e32 v58, vcc, s33, v48
	v_lshl_add_u64 v[14:15], v[2:3], 0, v[20:21]
	v_lshl_add_u64 v[44:45], s[42:43], 0, v[0:1]
	v_lshlrev_b32_e32 v66, 1, v6
	v_mov_b32_e32 v67, v21
	v_addc_co_u32_e32 v59, vcc, 0, v49, vcc
	global_load_ushort v2, v[14:15], off offset:832
	global_load_ushort v3, v[4:5], off offset:832
	v_lshl_add_u64 v[0:1], v[44:45], 0, v[66:67]
	s_movk_i32 s0, 0x4000
	global_load_ushort v6, v[0:1], off
	v_add_co_u32_e32 v46, vcc, s0, v48
	v_max_i32_e32 v0, 3, v41
	s_nop 0
	v_addc_co_u32_e32 v47, vcc, 0, v49, vcc
	global_load_dword v65, v[58:59], off
	global_load_dword v64, v[46:47], off offset:2048
	v_add3_u32 v0, s41, -3, v0
	v_ashrrev_i32_e32 v1, 31, v0
	v_lshlrev_b64 v[0:1], 12, v[0:1]
	v_lshl_add_u64 v[56:57], s[42:43], 0, v[0:1]
	v_lshl_add_u64 v[234:235], v[56:57], 0, v[20:21]
	global_load_ushort v230, v[234:235], off offset:832
	v_or_b32_e32 v236, 1, v41
	v_cndmask_b32_e64 v236, 0, v236, s[34:35]
	v_add_u32_e32 v236, s41, v236
	v_ashrrev_i32_e32 v237, 31, v236
	v_lshlrev_b64 v[236:237], 12, v[236:237]
	v_lshl_add_u64 v[236:237], s[42:43], 0, v[236:237]
	v_lshl_add_u64 v[236:237], v[236:237], 0, v[66:67]
	global_load_ushort v231, v[236:237], off
	v_or_b32_e32 v236, 2, v41
	v_cndmask_b32_e64 v236, 0, v236, s[34:35]
	v_add_u32_e32 v236, s41, v236
	v_ashrrev_i32_e32 v237, 31, v236
	v_lshlrev_b64 v[236:237], 12, v[236:237]
	v_lshl_add_u64 v[236:237], s[42:43], 0, v[236:237]
	v_lshl_add_u64 v[236:237], v[236:237], 0, v[66:67]
	global_load_ushort v232, v[236:237], off
	v_or_b32_e32 v236, 3, v41
	v_cndmask_b32_e64 v236, 0, v236, s[34:35]
	v_add_u32_e32 v236, s41, v236
	v_ashrrev_i32_e32 v237, 31, v236
	v_lshlrev_b64 v[236:237], 12, v[236:237]
	v_lshl_add_u64 v[236:237], s[42:43], 0, v[236:237]
	v_lshl_add_u64 v[236:237], v[236:237], 0, v[66:67]
	global_load_ushort v233, v[236:237], off
	v_cmp_lt_i32_e64 s[28:29], 0, v41
	v_cmp_lt_i32_e64 s[30:31], 1, v41
	v_cmp_lt_i32_e32 vcc, 2, v41
	v_cmp_gt_i32_e64 s[36:37], 0, v41
	s_waitcnt vmcnt(8)
	v_lshlrev_b32_e32 v1, 16, v2
	s_waitcnt vmcnt(7)
	v_lshlrev_b32_e32 v0, 16, v3
	v_cndmask_b32_e64 v3, 0, v1, s[28:29]
	v_cndmask_b32_e64 v2, 0, v0, s[30:31]
	s_waitcnt vmcnt(6)
	v_lshlrev_b32_e32 v8, 16, v6
	v_mov_b32_e32 v0, v21
	s_and_saveexec_b64 s[0:1], s[34:35]
	s_cbranch_execz .LBB0_2862
	v_lshl_add_u64 v[0:1], v[56:57], 0, v[20:21]
	v_mov_b32_e32 v0, v2
	v_mov_b32_e32 v9, v3
	s_waitcnt vmcnt(4)
	v_pk_mul_f32 v[6:7], v[64:65], v[8:9]
	s_waitcnt vmcnt(3)
	v_lshlrev_b32_e32 v1, 16, v230
	v_cndmask_b32_e32 v1, 0, v1, vcc
	v_pk_mul_f32 v[0:1], v[62:63], v[0:1]
	s_nop 0
	v_add_f32_e32 v0, v0, v1
	v_add_f32_e32 v0, v7, v0
	v_add_f32_e32 v0, v6, v0
	v_mul_f32_e32 v1, 0xbfb8aa3b, v0
	v_exp_f32_e32 v1, v1
	s_nop 0
	v_add_f32_e32 v1, 1.0, v1
	v_rcp_f32_e32 v1, v1
	s_nop 0
	v_mul_f32_e32 v0, v0, v1

.LBB0_2872:
	s_or_b64 exec, exec, s[36:37]
	v_add_u32_e32 v0, 0x8000, v90
	ds_write2_b32 v0, v54, v55 offset0:128 offset1:193
	v_add_u32_e32 v0, 0x8400, v90
	ds_write2_b32 v0, v61, v60 offset0:2 offset1:67
	ds_write2_b32 v0, v7, v6 offset0:132 offset1:197
	v_add_u32_e32 v0, 0x8800, v90
	ds_write2_b32 v0, v11, v10 offset0:6 offset1:71
	s_and_saveexec_b64 s[0:1], s[2:3]
	s_cbranch_execz .LBB0_2876
	v_add_u32_e32 v2, s46, v208
	v_cmp_lt_i32_e32 vcc, -1, v2
	v_mov_b32_e32 v1, 0
	v_mov_b32_e32 v0, 0
	s_and_saveexec_b64 s[28:29], vcc
	s_cbranch_execz .LBB0_2875
	v_add_u32_e32 v0, s41, v2
	v_ashrrev_i32_e32 v1, 31, v0
	v_lshlrev_b64 v[0:1], 6, v[0:1]
	v_lshl_add_u64 v[0:1], s[78:79], 0, v[0:1]
	s_lshl_b32 s76, s40, 2
	v_lshl_add_u64 v[0:1], v[0:1], 0, s[76:77]
	v_mov_b32_e32 v2, s76
	s_nop 0
	s_nop 0
	s_nop 0
	s_mov_b32 s30, 0x3f317217
	s_waitcnt vmcnt(0)
	v_mul_f32_e32 v1, 0x3fb8aa3b, v253
	v_add_f32_e32 v2, v242, v252
	v_mul_f32_e32 v3, 0x3fb8aa3b, v2
	v_exp_f32_e32 v3, v3
	v_mul_f32_e32 v0, 0xbfb8aa3b, v243
	v_exp_f32_e32 v0, v0
	v_exp_f32_e32 v1, v1
	v_add_f32_e32 v3, 1.0, v3
	v_cmp_gt_f32_e32 vcc, s64, v3
	v_add_f32_e32 v0, 1.0, v0
	v_rcp_f32_e32 v0, v0
	v_cndmask_b32_e64 v4, 0, 32, vcc
	v_ldexp_f32 v3, v3, v4
	v_log_f32_e32 v3, v3
	v_cndmask_b32_e32 v4, 0, v181, vcc
	v_mul_f32_e32 v5, 0x3f317217, v3
	v_fma_f32 v5, v3, s30, -v5
	v_fmac_f32_e32 v5, 0x3377d1cf, v3
	s_mov_b32 s30, 0x7f800000
	v_fmac_f32_e32 v5, 0x3f317217, v3
	v_cmp_lt_f32_e64 vcc, |v3|, s30
	s_mov_b32 s30, 0x41a00000
	s_nop 0
	v_cndmask_b32_e32 v3, v3, v5, vcc
	v_sub_f32_e32 v3, v3, v4
	v_cmp_lt_f32_e32 vcc, s30, v2
	s_nop 1
	v_cndmask_b32_e32 v2, v3, v2, vcc
	v_mul_f32_e64 v1, v2, -v1

.LBB0_2878:
	s_or_b64 exec, exec, s[0:1]
	v_mov_b32_e32 v15, 0
	v_mov_b32_e32 v41, 0
	v_mov_b32_e32 v14, v15
	v_mov_b32_e32 v13, v15
	v_mov_b32_e32 v12, v15
	v_mov_b32_e32 v11, v15
	v_mov_b32_e32 v10, v15
	v_mov_b32_e32 v9, v15
	v_mov_b32_e32 v8, v15
	v_mov_b32_e32 v7, v15
	v_mov_b32_e32 v6, v15
	v_mov_b32_e32 v5, v15
	v_mov_b32_e32 v4, v15
	v_mov_b32_e32 v3, v15
	v_mov_b32_e32 v2, v15
	v_mov_b32_e32 v1, v15
	v_mov_b32_e32 v0, v15
	v_mov_b32_e32 v20, v78
	s_waitcnt lgkmcnt(0)
	s_barrier
	s_and_saveexec_b64 s[0:1], s[80:81]
	s_cbranch_execz .LBB0_2882
	v_mov_b32_e32 v0, 0
	s_mov_b32 s28, 0
	v_mov_b32_e32 v1, v0
	v_mov_b32_e32 v2, v0
	v_mov_b32_e32 v3, v0
	v_mov_b32_e32 v4, v0
	v_mov_b32_e32 v5, v0
	v_mov_b32_e32 v6, v0
	v_mov_b32_e32 v7, v0
	v_mov_b32_e32 v8, v0
	v_mov_b32_e32 v9, v0
	v_mov_b32_e32 v10, v0
	v_mov_b32_e32 v11, v0
	v_mov_b32_e32 v12, v0
	v_mov_b32_e32 v13, v0
	v_mov_b32_e32 v14, v0
	v_mov_b32_e32 v15, v0
	ds_read2_b32 v[44:45], v76 offset0:0 offset1:2
	ds_read2_b32 v[46:47], v89 offset0:0 offset1:2
	ds_read2_b32 v[48:49], v76 offset0:4 offset1:6
	ds_read2_b32 v[50:51], v89 offset0:4 offset1:6
	ds_read2_b32 v[52:53], v76 offset0:8 offset1:10
	ds_read2_b32 v[54:55], v89 offset0:8 offset1:10
	ds_read2_b32 v[56:57], v76 offset0:12 offset1:14
	ds_read2_b32 v[58:59], v89 offset0:12 offset1:14
	ds_read2_b32 v[60:61], v76 offset0:16 offset1:18
	ds_read2_b32 v[62:63], v89 offset0:16 offset1:18
	ds_read2_b32 v[64:65], v76 offset0:20 offset1:22
	ds_read2_b32 v[66:67], v89 offset0:20 offset1:22
	ds_read2_b32 v[184:185], v76 offset0:24 offset1:26
	ds_read2_b32 v[186:187], v89 offset0:24 offset1:26
	s_waitcnt lgkmcnt(12)
	v_mfma_f32_32x32x2_f32 v[0:15], v44, v46, v[0:15]
	v_mfma_f32_32x32x2_f32 v[0:15], v45, v47, v[0:15]
	ds_read2_b32 v[188:189], v76 offset0:28 offset1:30
	ds_read2_b32 v[190:191], v89 offset0:28 offset1:30
	s_waitcnt lgkmcnt(12)
	v_mfma_f32_32x32x2_f32 v[0:15], v48, v50, v[0:15]
	v_mfma_f32_32x32x2_f32 v[0:15], v49, v51, v[0:15]
	ds_read2_b32 v[44:45], v76 offset0:32 offset1:34
	ds_read2_b32 v[46:47], v89 offset0:32 offset1:34
	s_waitcnt lgkmcnt(12)
	v_mfma_f32_32x32x2_f32 v[0:15], v52, v54, v[0:15]
	v_mfma_f32_32x32x2_f32 v[0:15], v53, v55, v[0:15]
	ds_read2_b32 v[48:49], v76 offset0:36 offset1:38
	ds_read2_b32 v[50:51], v89 offset0:36 offset1:38
	s_waitcnt lgkmcnt(12)
	v_mfma_f32_32x32x2_f32 v[0:15], v56, v58, v[0:15]
	v_mfma_f32_32x32x2_f32 v[0:15], v57, v59, v[0:15]
	ds_read2_b32 v[52:53], v76 offset0:40 offset1:42
	ds_read2_b32 v[54:55], v89 offset0:40 offset1:42
	s_waitcnt lgkmcnt(12)
	v_mfma_f32_32x32x2_f32 v[0:15], v60, v62, v[0:15]
	v_mfma_f32_32x32x2_f32 v[0:15], v61, v63, v[0:15]
	ds_read2_b32 v[56:57], v76 offset0:44 offset1:46
	ds_read2_b32 v[58:59], v89 offset0:44 offset1:46
	s_waitcnt lgkmcnt(12)
	v_mfma_f32_32x32x2_f32 v[0:15], v64, v66, v[0:15]
	v_mfma_f32_32x32x2_f32 v[0:15], v65, v67, v[0:15]
	ds_read2_b32 v[60:61], v76 offset0:48 offset1:50
	ds_read2_b32 v[62:63], v89 offset0:48 offset1:50
	s_waitcnt lgkmcnt(12)
	v_mfma_f32_32x32x2_f32 v[0:15], v184, v186, v[0:15]
	v_mfma_f32_32x32x2_f32 v[0:15], v185, v187, v[0:15]
	ds_read2_b32 v[64:65], v76 offset0:52 offset1:54
	ds_read2_b32 v[66:67], v89 offset0:52 offset1:54
	s_waitcnt lgkmcnt(12)
	v_mfma_f32_32x32x2_f32 v[0:15], v188, v190, v[0:15]
	v_mfma_f32_32x32x2_f32 v[0:15], v189, v191, v[0:15]
	ds_read2_b32 v[184:185], v76 offset0:56 offset1:58
	ds_read2_b32 v[186:187], v89 offset0:56 offset1:58
	s_waitcnt lgkmcnt(12)
	v_mfma_f32_32x32x2_f32 v[0:15], v44, v46, v[0:15]
	v_mfma_f32_32x32x2_f32 v[0:15], v45, v47, v[0:15]
	ds_read2_b32 v[188:189], v76 offset0:60 offset1:62
	ds_read2_b32 v[190:191], v89 offset0:60 offset1:62
	s_waitcnt lgkmcnt(12)
	v_mfma_f32_32x32x2_f32 v[0:15], v48, v50, v[0:15]
	v_mfma_f32_32x32x2_f32 v[0:15], v49, v51, v[0:15]
	s_waitcnt lgkmcnt(10)
	v_mfma_f32_32x32x2_f32 v[0:15], v52, v54, v[0:15]
	v_mfma_f32_32x32x2_f32 v[0:15], v53, v55, v[0:15]
	s_waitcnt lgkmcnt(8)
	v_mfma_f32_32x32x2_f32 v[0:15], v56, v58, v[0:15]
	v_mfma_f32_32x32x2_f32 v[0:15], v57, v59, v[0:15]
	s_waitcnt lgkmcnt(6)
	v_mfma_f32_32x32x2_f32 v[0:15], v60, v62, v[0:15]
	v_mfma_f32_32x32x2_f32 v[0:15], v61, v63, v[0:15]
	s_waitcnt lgkmcnt(4)
	v_mfma_f32_32x32x2_f32 v[0:15], v64, v66, v[0:15]
	v_mfma_f32_32x32x2_f32 v[0:15], v65, v67, v[0:15]
	s_waitcnt lgkmcnt(2)
	v_mfma_f32_32x32x2_f32 v[0:15], v184, v186, v[0:15]
	v_mfma_f32_32x32x2_f32 v[0:15], v185, v187, v[0:15]
	s_waitcnt lgkmcnt(0)
	v_mfma_f32_32x32x2_f32 v[0:15], v188, v190, v[0:15]
	v_mfma_f32_32x32x2_f32 v[0:15], v189, v191, v[0:15]
	v_mov_b32_e32 v41, v74
	v_mov_b32_e32 v20, v77
